# scan loop: LDS operand reads issued before the LDS-DMA pieces, counted lgkmcnt, probe branches removed
# baseline (speedup 1.0000x reference)
.LBB0_1504:
	s_and_b64 vcc, exec, s[22:23]
	s_cbranch_vccz .Lsc_wlo
	s_waitcnt vmcnt(17)
	s_branch .Lsc_wdone
.Lsc_wlo:
	s_waitcnt vmcnt(20)
.Lsc_wdone:
	s_barrier
	s_and_b32 s26, 0xffff, s35
	s_mul_i32 s26, s26, 0xcccd
	s_lshr_b32 s26, s26, 18
	s_mul_i32 s26, s26, 5
	s_sub_i32 s26, s35, s26
	s_and_b32 s26, s26, 0xffff
	s_mulk_i32 s26, 0x6a00
	v_add_u32_e32 v46, s26, v157
	v_add_u32_e32 v42, s26, v159
	v_add_u32_e32 v47, v46, v167
	ds_read_b128 v[42:45], v42 offset:16384
	ds_read_b128 v[134:137], v47
	v_add_u32_e32 v48, v46, v166
	ds_read_b128 v[138:141], v47 offset:4096
	ds_read_b128 v[126:129], v48
	v_add_u32_e32 v47, v46, v168
	ds_read_b128 v[130:133], v48 offset:4096
	ds_read_b128 v[118:121], v47
	v_add_u32_e32 v46, v46, v169
	ds_read_b128 v[122:125], v47 offset:4096
	ds_read_b128 v[114:117], v46
	ds_read_b128 v[110:113], v46 offset:4096
	s_and_b64 vcc, exec, s[12:13]
	s_cbranch_vccnz .LBB0_1531
	v_add_u32_e32 v6, s26, v160
	ds_read_b128 v[2:5], v6 offset:24576
	ds_read_b128 v[6:9], v6 offset:25600
.LBB0_1531:
	s_add_i32 s26, s26, 0
	v_add3_u32 v46, s26, v1, v158
	v_add_u32_e32 v50, s26, v156
	ds_read_b128 v[102:105], v46 offset:8192
	ds_read_b128 v[90:93], v46 offset:9216
	ds_read_b128 v[106:109], v50 offset:26624
	ds_read_b128 v[98:101], v50 offset:26688
	ds_read_b128 v[86:89], v46 offset:10240
	ds_read_b128 v[74:77], v46 offset:11264
	ds_read_b128 v[94:97], v50 offset:26752
	ds_read_b128 v[82:85], v50 offset:26816
	ds_read_b128 v[70:73], v46 offset:12288
	ds_read_b128 v[58:61], v46 offset:13312
	ds_read_b128 v[78:81], v50 offset:26880
	ds_read_b128 v[66:69], v50 offset:26944
	ds_read_b128 v[54:57], v46 offset:14336
	ds_read_b128 v[46:49], v46 offset:15360
	ds_read_b128 v[62:65], v50 offset:27008
	ds_read_b128 v[50:53], v50 offset:27072
	s_andn2_b64 vcc, exec, s[16:17]
	s_mov_b64 s[26:27], -1
	s_cbranch_vccnz .LBB0_1521
	s_cmpk_lt_u32 s35, 0x104
	s_cselect_b32 s28, s36, 0
	s_mov_b64 s[26:27], 0

.LBB0_1527:
	s_or_b64 exec, exec, s[28:29]
	v_cvt_pk_bf16_f32 v170, v10, v11
	v_cvt_pk_bf16_f32 v171, v12, v13
	v_cvt_pk_bf16_f32 v172, v14, v15
	v_cvt_pk_bf16_f32 v173, v16, v17
	s_and_b64 vcc, exec, s[12:13]
	s_waitcnt lgkmcnt(15)
	v_mfma_f32_16x16x32_bf16 v[134:137], v[170:173], v[134:137], 0
	v_mfma_f32_16x16x32_bf16 v[138:141], v[170:173], v[138:141], 0
	v_cvt_pk_bf16_f32 v170, v18, v19
	v_cvt_pk_bf16_f32 v171, v20, v21
	v_cvt_pk_bf16_f32 v172, v22, v23
	v_cvt_pk_bf16_f32 v173, v24, v25
	s_nop 0
	v_mfma_f32_16x16x32_bf16 v[126:129], v[170:173], v[126:129], v[134:137]
	v_cvt_pk_bf16_f32 v134, v26, v27
	v_cvt_pk_bf16_f32 v135, v28, v29
	v_cvt_pk_bf16_f32 v136, v30, v31
	v_mfma_f32_16x16x32_bf16 v[130:133], v[170:173], v[130:133], v[138:141]
	v_cvt_pk_bf16_f32 v137, v32, v33
	s_nop 3
	v_mfma_f32_16x16x32_bf16 v[118:121], v[134:137], v[118:121], v[126:129]
	v_cvt_pk_bf16_f32 v126, v34, v35
	v_cvt_pk_bf16_f32 v127, v36, v37
	v_cvt_pk_bf16_f32 v128, v38, v39
	v_mfma_f32_16x16x32_bf16 v[122:125], v[134:137], v[122:125], v[130:133]
	v_cvt_pk_bf16_f32 v129, v40, v41
	s_nop 0
	v_mfma_f32_16x16x32_bf16 v[114:117], v[126:129], v[114:117], v[118:121]
	v_mfma_f32_16x16x32_bf16 v[110:113], v[126:129], v[110:113], v[122:125]
	s_cbranch_vccnz .LBB0_1533
	v_mfma_f32_16x16x32_bf16 v[114:117], v[42:45], v[2:5], v[114:117]
	v_mfma_f32_16x16x32_bf16 v[110:113], v[42:45], v[6:9], v[110:113]
.LBB0_1533:
	s_add_i32 s28, s36, 4
	s_cmp_lt_u32 s35, 8
	s_cselect_b32 s26, 0x100, -8
	s_add_i32 s29, s26, s35
	s_and_b64 s[26:27], s[18:19], exec
	s_cselect_b32 s26, s29, s28
	s_lshl_b32 s26, s26, 5
	s_ashr_i32 s27, s26, 31
	v_lshl_add_u64 v[118:119], v[152:153], 0, s[26:27]
	v_mad_u64_u32 v[120:121], s[26:27], v118, s37, v[154:155]
	v_mov_b32_e32 v118, v121
	v_mad_u64_u32 v[118:119], s[26:27], v119, s37, v[118:119]
	v_mov_b32_e32 v121, v118
	v_cvt_pk_bf16_f32 v114, v114, v115
	v_cvt_pk_bf16_f32 v115, v116, v117
	global_store_dwordx2 v[120:121], v[114:115], off
	v_cvt_pk_bf16_f32 v110, v110, v111
	v_cvt_pk_bf16_f32 v111, v112, v113
	v_add_co_u32_e32 v112, vcc, 0x18000, v120
	s_nop 1
	v_addc_co_u32_e32 v113, vcc, 0, v118, vcc
	global_store_dwordx2 v[112:113], v[110:111], off
	s_waitcnt lgkmcnt(0)
	v_pk_mul_f32 v[12:13], v[12:13], v[108:109]
	v_pk_mul_f32 v[10:11], v[10:11], v[106:107]
	v_pk_mul_f32 v[16:17], v[16:17], v[100:101]
	v_pk_mul_f32 v[14:15], v[14:15], v[98:99]
	v_pk_mul_f32 v[20:21], v[20:21], v[96:97]
	v_pk_mul_f32 v[18:19], v[18:19], v[94:95]
	v_pk_mul_f32 v[24:25], v[24:25], v[84:85]
	v_pk_mul_f32 v[22:23], v[22:23], v[82:83]
	v_pk_mul_f32 v[28:29], v[28:29], v[80:81]
	v_pk_mul_f32 v[26:27], v[26:27], v[78:79]
	v_pk_mul_f32 v[32:33], v[32:33], v[68:69]
	v_pk_mul_f32 v[30:31], v[30:31], v[66:67]
	v_pk_mul_f32 v[36:37], v[36:37], v[64:65]
	v_pk_mul_f32 v[34:35], v[34:35], v[62:63]
	v_pk_mul_f32 v[40:41], v[40:41], v[52:53]
	v_pk_mul_f32 v[38:39], v[38:39], v[50:51]
	v_mfma_f32_16x16x32_bf16 v[10:13], v[102:105], v[42:45], v[10:13]
	v_mfma_f32_16x16x32_bf16 v[14:17], v[90:93], v[42:45], v[14:17]
	v_mfma_f32_16x16x32_bf16 v[18:21], v[86:89], v[42:45], v[18:21]
	v_mfma_f32_16x16x32_bf16 v[22:25], v[74:77], v[42:45], v[22:25]
	v_mfma_f32_16x16x32_bf16 v[26:29], v[70:73], v[42:45], v[26:29]
	v_mfma_f32_16x16x32_bf16 v[30:33], v[58:61], v[42:45], v[30:33]
	v_mfma_f32_16x16x32_bf16 v[34:37], v[54:57], v[42:45], v[34:37]
	v_mfma_f32_16x16x32_bf16 v[38:41], v[46:49], v[42:45], v[38:41]
	s_add_i32 s35, s35, 1
	s_add_i32 s36, s36, -1
	s_cmp_lg_u32 s36, -5
	s_cbranch_scc1 .LBB0_1504
